# phase-15 fast path: each packed f32 scale-and-bias fma split into two plain f32 fma (bit-identical), since packed f32 ops stall next to MFMAs
# speedup vs baseline: 1.0020x; 1.0020x over previous
; template <bool MASKED>
; __device__ __forceinline__ void nsa_online_step(NsaState& st, f32x4 (&s)[2][4], unsigned vmask, bool lanevalid, const u16* sV, int fr, int fq) {
;     ...
;     const float nb = -st.m[hh] * SM_C;
; #pragma unroll
;     for (int k2 = 0; k2 < 2; ++k2) {
;       uint32_t pw[4];
; #pragma unroll
;       for (int e2 = 0; e2 < 4; ++e2) {
;         const int mt = 2 * k2 + (e2 >> 1), j = (e2 & 1) * 2;
;         float p0 = __builtin_amdgcn_exp2f(__builtin_fmaf(s[hh][mt][j], SM_C, nb));
;         float p1 = __builtin_amdgcn_exp2f(__builtin_fmaf(s[hh][mt][j + 1], SM_C, nb));
;         if (MASKED) {
;           p0 = ((vmask >> (mt * 4 + j)) & 1u) ? p0 : 0.f;
;           p1 = ((vmask >> (mt * 4 + j + 1)) & 1u) ? p1 : 0.f;
;         }
;         pw[e2] = pack2(p0, p1);
.Lfp15_noupd0:
	v_mul_f32_e32 v2, 0xbe38aa3b, v234
	v_cndmask_b32_e64 v2, v221, v2, s[30:31]
	v_fma_f32 v136, v68, s20, v2
	v_fma_f32 v137, v69, s20, v2
	v_fma_f32 v138, v70, s20, v2
	v_fma_f32 v139, v71, s20, v2
	v_exp_f32_e32 v136, v136
	v_exp_f32_e32 v137, v137
	v_exp_f32_e32 v138, v138
	v_exp_f32_e32 v139, v139
	v_fma_f32 v140, v72, s20, v2
	v_fma_f32 v141, v73, s20, v2
	v_fma_f32 v142, v74, s20, v2
	v_fma_f32 v143, v75, s20, v2
	v_cvt_pk_bf16_f32 v236, v136, v137
	v_cvt_pk_bf16_f32 v237, v138, v139
	v_exp_f32_e32 v140, v140
	v_exp_f32_e32 v141, v141
	v_exp_f32_e32 v142, v142
	v_exp_f32_e32 v143, v143
	v_fma_f32 v144, v76, s20, v2
	v_fma_f32 v145, v77, s20, v2
	v_fma_f32 v146, v78, s20, v2
	v_fma_f32 v147, v79, s20, v2
	v_cvt_pk_bf16_f32 v238, v140, v141
	v_cvt_pk_bf16_f32 v239, v142, v143
	v_exp_f32_e32 v144, v144
	v_exp_f32_e32 v145, v145
	v_exp_f32_e32 v146, v146
	v_exp_f32_e32 v147, v147
	v_fma_f32 v148, v80, s20, v2
	v_fma_f32 v149, v81, s20, v2
	v_fma_f32 v150, v82, s20, v2
	v_fma_f32 v151, v83, s20, v2
	v_cvt_pk_bf16_f32 v240, v144, v145
	v_cvt_pk_bf16_f32 v241, v146, v147
	v_exp_f32_e32 v148, v148
	v_exp_f32_e32 v149, v149
	v_exp_f32_e32 v150, v150
	v_exp_f32_e32 v151, v151

; template <bool MASKED>
; __device__ __forceinline__ void nsa_online_step(NsaState& st, f32x4 (&s)[2][4], unsigned vmask, bool lanevalid, const u16* sV, int fr, int fq) {
;     ...
;     const float nb = -st.m[hh] * SM_C;
; #pragma unroll
;     for (int k2 = 0; k2 < 2; ++k2) {
;       uint32_t pw[4];
; #pragma unroll
;       for (int e2 = 0; e2 < 4; ++e2) {
;         const int mt = 2 * k2 + (e2 >> 1), j = (e2 & 1) * 2;
;         float p0 = __builtin_amdgcn_exp2f(__builtin_fmaf(s[hh][mt][j], SM_C, nb));
;         float p1 = __builtin_amdgcn_exp2f(__builtin_fmaf(s[hh][mt][j + 1], SM_C, nb));
;         if (MASKED) {
;           p0 = ((vmask >> (mt * 4 + j)) & 1u) ? p0 : 0.f;
;           p1 = ((vmask >> (mt * 4 + j + 1)) & 1u) ? p1 : 0.f;
;         }
;         pw[e2] = pack2(p0, p1);
;         if (!MASKED) pw[e2] &= lmask;
;       }
;       pf[hh][k2] = mk_frag(pw[0], pw[1], pw[2], pw[3]);
;       st.accL[hh] = mfma16(ones, pf[hh][k2], st.accL[hh]);
;     }
; #pragma unroll
;     for (int k2 = 0; k2 < 2; ++k2)
; #pragma unroll
;       for (int dm = 0; dm < 4; ++dm) {
;         const bf16x8 vf = *(const bf16x8*)(sV + (dm * 16 + fr) * LDSP + k2 * 32 + fq * 8);
;         st.acc[hh][dm] = mfma16(vf, pf[hh][k2], st.acc[hh][dm]);
;       }
.Lfp15_noupd1:
	v_mul_f32_e32 v2, 0xbe38aa3b, v235
	v_cndmask_b32_e64 v2, v221, v2, s[30:31]
	v_fma_f32 v136, v84, s20, v2
	v_fma_f32 v137, v85, s20, v2
	v_fma_f32 v138, v86, s20, v2
	v_fma_f32 v139, v87, s20, v2
	v_exp_f32_e32 v136, v136
	v_mfma_f32_16x16x32_bf16 v[48:51], v[20:23], v[240:243], v[48:51]
	v_exp_f32_e32 v137, v137
	v_exp_f32_e32 v138, v138
	v_exp_f32_e32 v139, v139
	v_fma_f32 v140, v88, s20, v2
	v_fma_f32 v141, v89, s20, v2
	v_mfma_f32_16x16x32_bf16 v[52:55], v[32:35], v[240:243], v[52:55]
	v_fma_f32 v142, v90, s20, v2
	v_fma_f32 v143, v91, s20, v2
	v_cvt_pk_bf16_f32 v244, v136, v137
	v_cvt_pk_bf16_f32 v245, v138, v139
	v_exp_f32_e32 v140, v140
	v_mfma_f32_16x16x32_bf16 v[56:59], v[40:43], v[240:243], v[56:59]
	v_exp_f32_e32 v141, v141
	v_exp_f32_e32 v142, v142
	v_exp_f32_e32 v143, v143
	v_fma_f32 v144, v92, s20, v2
	v_fma_f32 v145, v93, s20, v2
	v_mfma_f32_16x16x32_bf16 v[60:63], v[120:123], v[240:243], v[60:63]
	v_fma_f32 v146, v94, s20, v2
	v_fma_f32 v147, v95, s20, v2
	v_cvt_pk_bf16_f32 v246, v140, v141
	v_cvt_pk_bf16_f32 v247, v142, v143
	v_exp_f32_e32 v144, v144
	v_mfma_f32_16x16x32_bf16 v[64:67], v[128:131], v[240:243], v[64:67]
	v_exp_f32_e32 v145, v145
	v_exp_f32_e32 v146, v146
	v_exp_f32_e32 v147, v147
	v_fma_f32 v148, v96, s20, v2
	v_fma_f32 v149, v97, s20, v2
	v_fma_f32 v150, v98, s20, v2
	v_fma_f32 v151, v99, s20, v2
	v_cvt_pk_bf16_f32 v100, v144, v145
	v_cvt_pk_bf16_f32 v101, v146, v147
	v_exp_f32_e32 v148, v148
	v_exp_f32_e32 v149, v149
	v_exp_f32_e32 v150, v150
	v_exp_f32_e32 v151, v151
	s_nop 0
	v_cvt_pk_bf16_f32 v102, v148, v149
	v_cvt_pk_bf16_f32 v103, v150, v151
	s_nop 0
	v_mfma_f32_16x16x32_bf16 v[132:135], v[20:23], v[244:247], v[132:135]
	v_mfma_f32_16x16x32_bf16 v[116:119], v[28:31], v[244:247], v[116:119]
	v_mfma_f32_16x16x32_bf16 v[112:115], v[36:39], v[244:247], v[112:115]
	v_mfma_f32_16x16x32_bf16 v[108:111], v[44:47], v[244:247], v[108:111]
	v_mfma_f32_16x16x32_bf16 v[104:107], v[124:127], v[244:247], v[104:107]
	v_mfma_f32_16x16x32_bf16 v[132:135], v[20:23], v[100:103], v[132:135]
	v_mfma_f32_16x16x32_bf16 v[116:119], v[32:35], v[100:103], v[116:119]
	v_mfma_f32_16x16x32_bf16 v[112:115], v[40:43], v[100:103], v[112:115]
	v_mfma_f32_16x16x32_bf16 v[108:111], v[120:123], v[100:103], v[108:111]
	v_mfma_f32_16x16x32_bf16 v[104:107], v[128:131], v[100:103], v[104:107]
	s_branch .Lfp15_tail
